# batched causal-mask section plus attention staging wait moved from step A QK to step B LDS stores
# baseline (speedup 1.0000x reference)
.LBB0_1084:
	ds_read_b128 v[68:71], v234
	ds_read_b128 v[100:103], v234 offset:32
	ds_read_b128 v[72:75], v234 offset:8704
	ds_read_b128 v[104:107], v234 offset:8736
	ds_read_b128 v[108:111], v234 offset:64
	ds_read_b128 v[112:115], v234 offset:96
	ds_read_b128 v[116:119], v234 offset:8768
	ds_read_b128 v[120:123], v234 offset:8800
	s_waitcnt lgkmcnt(7)
	v_mfma_f32_32x32x16_bf16 v[84:99], v[68:71], v[140:143], 0
	ds_read_b64_tr_b16 v[176:177], v235 offset:17408
	ds_read_b64_tr_b16 v[172:173], v235 offset:17472
	ds_read_b64_tr_b16 v[168:169], v235 offset:17536
	ds_read_b64_tr_b16 v[164:165], v235 offset:17600
	ds_read_b64_tr_b16 v[178:179], v235 offset:19968
	ds_read_b64_tr_b16 v[174:175], v235 offset:20032
	ds_read_b64_tr_b16 v[170:171], v235 offset:20096
	ds_read_b64_tr_b16 v[166:167], v235 offset:20160
	s_waitcnt lgkmcnt(13)
	v_mfma_f32_32x32x16_bf16 v[68:83], v[72:75], v[140:143], 0
	v_mfma_f32_32x32x16_bf16 v[84:99], v[100:103], v[132:135], v[84:99]
	s_waitcnt lgkmcnt(12)
	v_mfma_f32_32x32x16_bf16 v[68:83], v[104:107], v[132:135], v[68:83]
	s_waitcnt lgkmcnt(11)
	v_mfma_f32_32x32x16_bf16 v[84:99], v[108:111], v[136:139], v[84:99]
	s_waitcnt lgkmcnt(9)
	v_mfma_f32_32x32x16_bf16 v[68:83], v[116:119], v[136:139], v[68:83]
	v_mfma_f32_32x32x16_bf16 v[84:99], v[112:115], v[144:147], v[84:99]
	s_waitcnt lgkmcnt(8)
	v_mfma_f32_32x32x16_bf16 v[68:83], v[120:123], v[144:147], v[68:83]
	s_cmp_lt_i32 s52, s50
	s_cbranch_scc1 .LBB0_1150
	s_mov_b32 s98, 0x12800
	s_mov_b32 s99, 0x12780
	v_mov_b32_e32 v246, 0xf149f2ca
	v_add_u32_e32 v243, 0, v67
	v_min_u32_e32 v244, 0x7f, v243
	v_min_u32_e32 v245, 0x9f, v243
	v_lshl_add_u32 v244, v244, 2, s98
	v_lshl_add_u32 v245, v245, 2, s99
	ds_read_b32 v116, v244
	ds_read_b32 v100, v245
	v_add_u32_e32 v243, -1, v67
	v_min_u32_e32 v244, 0x7f, v243
	v_min_u32_e32 v245, 0x9f, v243
	v_lshl_add_u32 v244, v244, 2, s98
	v_lshl_add_u32 v245, v245, 2, s99
	ds_read_b32 v117, v244
	ds_read_b32 v101, v245
	v_add_u32_e32 v243, -2, v67
	v_min_u32_e32 v244, 0x7f, v243
	v_min_u32_e32 v245, 0x9f, v243
	v_lshl_add_u32 v244, v244, 2, s98
	v_lshl_add_u32 v245, v245, 2, s99
	ds_read_b32 v118, v244
	ds_read_b32 v102, v245
	v_add_u32_e32 v243, -3, v67
	v_min_u32_e32 v244, 0x7f, v243
	v_min_u32_e32 v245, 0x9f, v243
	v_lshl_add_u32 v244, v244, 2, s98
	v_lshl_add_u32 v245, v245, 2, s99
	ds_read_b32 v119, v244
	ds_read_b32 v103, v245
	v_add_u32_e32 v243, -8, v67
	v_min_u32_e32 v244, 0x7f, v243
	v_min_u32_e32 v245, 0x9f, v243
	v_lshl_add_u32 v244, v244, 2, s98
	v_lshl_add_u32 v245, v245, 2, s99
	ds_read_b32 v120, v244
	ds_read_b32 v104, v245
	v_add_u32_e32 v243, -9, v67
	v_min_u32_e32 v244, 0x7f, v243
	v_min_u32_e32 v245, 0x9f, v243
	v_lshl_add_u32 v244, v244, 2, s98
	v_lshl_add_u32 v245, v245, 2, s99
	ds_read_b32 v121, v244
	ds_read_b32 v105, v245
	v_add_u32_e32 v243, -10, v67
	v_min_u32_e32 v244, 0x7f, v243
	v_min_u32_e32 v245, 0x9f, v243
	v_lshl_add_u32 v244, v244, 2, s98
	v_lshl_add_u32 v245, v245, 2, s99
	ds_read_b32 v122, v244
	ds_read_b32 v106, v245
	v_add_u32_e32 v243, -11, v67
	v_min_u32_e32 v244, 0x7f, v243
	v_min_u32_e32 v245, 0x9f, v243
	v_lshl_add_u32 v244, v244, 2, s98
	v_lshl_add_u32 v245, v245, 2, s99
	ds_read_b32 v123, v244
	ds_read_b32 v107, v245
	v_add_u32_e32 v243, -16, v67
	v_min_u32_e32 v244, 0x7f, v243
	v_min_u32_e32 v245, 0x9f, v243
	v_lshl_add_u32 v244, v244, 2, s98
	v_lshl_add_u32 v245, v245, 2, s99
	ds_read_b32 v124, v244
	ds_read_b32 v108, v245
	v_add_u32_e32 v243, 0xffffffef, v67
	v_min_u32_e32 v244, 0x7f, v243
	v_min_u32_e32 v245, 0x9f, v243
	v_lshl_add_u32 v244, v244, 2, s98
	v_lshl_add_u32 v245, v245, 2, s99
	ds_read_b32 v125, v244
	ds_read_b32 v109, v245
	v_add_u32_e32 v243, 0xffffffee, v67
	v_min_u32_e32 v244, 0x7f, v243
	v_min_u32_e32 v245, 0x9f, v243
	v_lshl_add_u32 v244, v244, 2, s98
	v_lshl_add_u32 v245, v245, 2, s99
	ds_read_b32 v126, v244
	ds_read_b32 v110, v245
	v_add_u32_e32 v243, 0xffffffed, v67
	v_min_u32_e32 v244, 0x7f, v243
	v_min_u32_e32 v245, 0x9f, v243
	v_lshl_add_u32 v244, v244, 2, s98
	v_lshl_add_u32 v245, v245, 2, s99
	ds_read_b32 v127, v244
	ds_read_b32 v111, v245
	v_add_u32_e32 v243, 0xffffffe8, v67
	v_min_u32_e32 v244, 0x7f, v243
	v_min_u32_e32 v245, 0x9f, v243
	v_lshl_add_u32 v244, v244, 2, s98
	v_lshl_add_u32 v245, v245, 2, s99
	ds_read_b32 v128, v244
	ds_read_b32 v112, v245
	v_add_u32_e32 v243, 0xffffffe7, v67
	v_min_u32_e32 v244, 0x7f, v243
	v_min_u32_e32 v245, 0x9f, v243
	v_lshl_add_u32 v244, v244, 2, s98
	v_lshl_add_u32 v245, v245, 2, s99
	ds_read_b32 v129, v244
	ds_read_b32 v113, v245
	v_add_u32_e32 v243, 0xffffffe6, v67
	v_min_u32_e32 v244, 0x7f, v243
	v_min_u32_e32 v245, 0x9f, v243
	v_lshl_add_u32 v244, v244, 2, s98
	v_lshl_add_u32 v245, v245, 2, s99
	ds_read_b32 v130, v244
	ds_read_b32 v114, v245
	v_add_u32_e32 v243, 0xffffffe5, v67
	v_min_u32_e32 v244, 0x7f, v243
	v_min_u32_e32 v245, 0x9f, v243
	v_lshl_add_u32 v244, v244, 2, s98
	v_lshl_add_u32 v245, v245, 2, s99
	ds_read_b32 v131, v244
	ds_read_b32 v115, v245
	s_waitcnt lgkmcnt(0)
	v_add_u32_e32 v243, 0, v67
	v_add_f32_e32 v116, v84, v116
	v_cmp_lt_i32_e32 vcc, -1, v243
	v_cndmask_b32_e32 v116, v246, v116, vcc
	v_add_f32_e32 v100, v68, v100
	v_cmp_lt_i32_e32 vcc, 31, v243
	v_cndmask_b32_e32 v100, v246, v100, vcc
	v_add_u32_e32 v243, -1, v67
	v_add_f32_e32 v117, v85, v117
	v_cmp_lt_i32_e32 vcc, -1, v243
	v_cndmask_b32_e32 v117, v246, v117, vcc
	v_add_f32_e32 v101, v69, v101
	v_cmp_lt_i32_e32 vcc, 31, v243
	v_cndmask_b32_e32 v101, v246, v101, vcc
	v_add_u32_e32 v243, -2, v67
	v_add_f32_e32 v118, v86, v118
	v_cmp_lt_i32_e32 vcc, -1, v243
	v_cndmask_b32_e32 v118, v246, v118, vcc
	v_add_f32_e32 v102, v70, v102
	v_cmp_lt_i32_e32 vcc, 31, v243
	v_cndmask_b32_e32 v102, v246, v102, vcc
	v_add_u32_e32 v243, -3, v67
	v_add_f32_e32 v119, v87, v119
	v_cmp_lt_i32_e32 vcc, -1, v243
	v_cndmask_b32_e32 v119, v246, v119, vcc
	v_add_f32_e32 v103, v71, v103
	v_cmp_lt_i32_e32 vcc, 31, v243
	v_cndmask_b32_e32 v103, v246, v103, vcc
	v_add_u32_e32 v243, -8, v67
	v_add_f32_e32 v120, v88, v120
	v_cmp_lt_i32_e32 vcc, -1, v243
	v_cndmask_b32_e32 v120, v246, v120, vcc
	v_add_f32_e32 v104, v72, v104
	v_cmp_lt_i32_e32 vcc, 31, v243
	v_cndmask_b32_e32 v104, v246, v104, vcc
	v_add_u32_e32 v243, -9, v67
	v_add_f32_e32 v121, v89, v121
	v_cmp_lt_i32_e32 vcc, -1, v243
	v_cndmask_b32_e32 v121, v246, v121, vcc
	v_add_f32_e32 v105, v73, v105
	v_cmp_lt_i32_e32 vcc, 31, v243
	v_cndmask_b32_e32 v105, v246, v105, vcc
	v_add_u32_e32 v243, -10, v67
	v_add_f32_e32 v122, v90, v122
	v_cmp_lt_i32_e32 vcc, -1, v243
	v_cndmask_b32_e32 v122, v246, v122, vcc
	v_add_f32_e32 v106, v74, v106
	v_cmp_lt_i32_e32 vcc, 31, v243
	v_cndmask_b32_e32 v106, v246, v106, vcc
	v_add_u32_e32 v243, -11, v67
	v_add_f32_e32 v123, v91, v123
	v_cmp_lt_i32_e32 vcc, -1, v243
	v_cndmask_b32_e32 v123, v246, v123, vcc
	v_add_f32_e32 v107, v75, v107
	v_cmp_lt_i32_e32 vcc, 31, v243
	v_cndmask_b32_e32 v107, v246, v107, vcc
	v_add_u32_e32 v243, -16, v67
	v_add_f32_e32 v124, v92, v124
	v_cmp_lt_i32_e32 vcc, -1, v243
	v_cndmask_b32_e32 v124, v246, v124, vcc
	v_add_f32_e32 v108, v76, v108
	v_cmp_lt_i32_e32 vcc, 31, v243
	v_cndmask_b32_e32 v108, v246, v108, vcc
	v_add_u32_e32 v243, 0xffffffef, v67
	v_add_f32_e32 v125, v93, v125
	v_cmp_lt_i32_e32 vcc, -1, v243
	v_cndmask_b32_e32 v125, v246, v125, vcc
	v_add_f32_e32 v109, v77, v109
	v_cmp_lt_i32_e32 vcc, 31, v243
	v_cndmask_b32_e32 v109, v246, v109, vcc
	v_add_u32_e32 v243, 0xffffffee, v67
	v_add_f32_e32 v126, v94, v126
	v_cmp_lt_i32_e32 vcc, -1, v243
	v_cndmask_b32_e32 v126, v246, v126, vcc
	v_add_f32_e32 v110, v78, v110
	v_cmp_lt_i32_e32 vcc, 31, v243
	v_cndmask_b32_e32 v110, v246, v110, vcc
	v_add_u32_e32 v243, 0xffffffed, v67
	v_add_f32_e32 v127, v95, v127
	v_cmp_lt_i32_e32 vcc, -1, v243
	v_cndmask_b32_e32 v127, v246, v127, vcc
	v_add_f32_e32 v111, v79, v111
	v_cmp_lt_i32_e32 vcc, 31, v243
	v_cndmask_b32_e32 v111, v246, v111, vcc
	v_add_u32_e32 v243, 0xffffffe8, v67
	v_add_f32_e32 v128, v96, v128
	v_cmp_lt_i32_e32 vcc, -1, v243
	v_cndmask_b32_e32 v128, v246, v128, vcc
	v_add_f32_e32 v112, v80, v112
	v_cmp_lt_i32_e32 vcc, 31, v243
	v_cndmask_b32_e32 v112, v246, v112, vcc
	v_add_u32_e32 v243, 0xffffffe7, v67
	v_add_f32_e32 v129, v97, v129
	v_cmp_lt_i32_e32 vcc, -1, v243
	v_cndmask_b32_e32 v129, v246, v129, vcc
	v_add_f32_e32 v113, v81, v113
	v_cmp_lt_i32_e32 vcc, 31, v243
	v_cndmask_b32_e32 v113, v246, v113, vcc
	v_add_u32_e32 v243, 0xffffffe6, v67
	v_add_f32_e32 v130, v98, v130
	v_cmp_lt_i32_e32 vcc, -1, v243
	v_cndmask_b32_e32 v130, v246, v130, vcc
	v_add_f32_e32 v114, v82, v114
	v_cmp_lt_i32_e32 vcc, 31, v243
	v_cndmask_b32_e32 v114, v246, v114, vcc
	v_add_u32_e32 v243, 0xffffffe5, v67
	v_add_f32_e32 v131, v99, v131
	v_cmp_lt_i32_e32 vcc, -1, v243
	v_cndmask_b32_e32 v131, v246, v131, vcc
	v_add_f32_e32 v115, v83, v115
	v_cmp_lt_i32_e32 vcc, 31, v243
	v_cndmask_b32_e32 v115, v246, v115, vcc

.LBB0_2344:
	ds_read_b128 v[68:71], v234
	ds_read_b128 v[100:103], v234 offset:32
	ds_read_b128 v[72:75], v234 offset:8704
	ds_read_b128 v[104:107], v234 offset:8736
	ds_read_b128 v[108:111], v234 offset:64
	ds_read_b128 v[112:115], v234 offset:96
	ds_read_b128 v[116:119], v234 offset:8768
	ds_read_b128 v[120:123], v234 offset:8800
	s_waitcnt lgkmcnt(7)
	v_mfma_f32_32x32x16_bf16 v[84:99], v[68:71], v[140:143], 0
	ds_read_b64_tr_b16 v[176:177], v235 offset:17408
	ds_read_b64_tr_b16 v[172:173], v235 offset:17472
	ds_read_b64_tr_b16 v[168:169], v235 offset:17536
	ds_read_b64_tr_b16 v[164:165], v235 offset:17600
	ds_read_b64_tr_b16 v[178:179], v235 offset:19968
	ds_read_b64_tr_b16 v[174:175], v235 offset:20032
	ds_read_b64_tr_b16 v[170:171], v235 offset:20096
	ds_read_b64_tr_b16 v[166:167], v235 offset:20160
	s_waitcnt lgkmcnt(13)
	v_mfma_f32_32x32x16_bf16 v[68:83], v[72:75], v[140:143], 0
	v_mfma_f32_32x32x16_bf16 v[84:99], v[100:103], v[132:135], v[84:99]
	s_waitcnt lgkmcnt(12)
	v_mfma_f32_32x32x16_bf16 v[68:83], v[104:107], v[132:135], v[68:83]
	s_waitcnt lgkmcnt(11)
	v_mfma_f32_32x32x16_bf16 v[84:99], v[108:111], v[136:139], v[84:99]
	s_waitcnt lgkmcnt(9)
	v_mfma_f32_32x32x16_bf16 v[68:83], v[116:119], v[136:139], v[68:83]
	v_mfma_f32_32x32x16_bf16 v[84:99], v[112:115], v[144:147], v[84:99]
	s_waitcnt lgkmcnt(8)
	v_mfma_f32_32x32x16_bf16 v[68:83], v[120:123], v[144:147], v[68:83]
	s_cmp_lt_i32 s69, s67
	s_cbranch_scc1 .LBB0_2410
	s_mov_b32 s98, 0x12800
	s_mov_b32 s99, 0x12780
	v_mov_b32_e32 v246, 0xf149f2ca
	v_add_u32_e32 v243, 0, v67
	v_min_u32_e32 v244, 0x7f, v243
	v_min_u32_e32 v245, 0x9f, v243
	v_lshl_add_u32 v244, v244, 2, s98
	v_lshl_add_u32 v245, v245, 2, s99
	ds_read_b32 v116, v244
	ds_read_b32 v100, v245
	v_add_u32_e32 v243, -1, v67
	v_min_u32_e32 v244, 0x7f, v243
	v_min_u32_e32 v245, 0x9f, v243
	v_lshl_add_u32 v244, v244, 2, s98
	v_lshl_add_u32 v245, v245, 2, s99
	ds_read_b32 v117, v244
	ds_read_b32 v101, v245
	v_add_u32_e32 v243, -2, v67
	v_min_u32_e32 v244, 0x7f, v243
	v_min_u32_e32 v245, 0x9f, v243
	v_lshl_add_u32 v244, v244, 2, s98
	v_lshl_add_u32 v245, v245, 2, s99
	ds_read_b32 v118, v244
	ds_read_b32 v102, v245
	v_add_u32_e32 v243, -3, v67
	v_min_u32_e32 v244, 0x7f, v243
	v_min_u32_e32 v245, 0x9f, v243
	v_lshl_add_u32 v244, v244, 2, s98
	v_lshl_add_u32 v245, v245, 2, s99
	ds_read_b32 v119, v244
	ds_read_b32 v103, v245
	v_add_u32_e32 v243, -8, v67
	v_min_u32_e32 v244, 0x7f, v243
	v_min_u32_e32 v245, 0x9f, v243
	v_lshl_add_u32 v244, v244, 2, s98
	v_lshl_add_u32 v245, v245, 2, s99
	ds_read_b32 v120, v244
	ds_read_b32 v104, v245
	v_add_u32_e32 v243, -9, v67
	v_min_u32_e32 v244, 0x7f, v243
	v_min_u32_e32 v245, 0x9f, v243
	v_lshl_add_u32 v244, v244, 2, s98
	v_lshl_add_u32 v245, v245, 2, s99
	ds_read_b32 v121, v244
	ds_read_b32 v105, v245
	v_add_u32_e32 v243, -10, v67
	v_min_u32_e32 v244, 0x7f, v243
	v_min_u32_e32 v245, 0x9f, v243
	v_lshl_add_u32 v244, v244, 2, s98
	v_lshl_add_u32 v245, v245, 2, s99
	ds_read_b32 v122, v244
	ds_read_b32 v106, v245
	v_add_u32_e32 v243, -11, v67
	v_min_u32_e32 v244, 0x7f, v243
	v_min_u32_e32 v245, 0x9f, v243
	v_lshl_add_u32 v244, v244, 2, s98
	v_lshl_add_u32 v245, v245, 2, s99
	ds_read_b32 v123, v244
	ds_read_b32 v107, v245
	v_add_u32_e32 v243, -16, v67
	v_min_u32_e32 v244, 0x7f, v243
	v_min_u32_e32 v245, 0x9f, v243
	v_lshl_add_u32 v244, v244, 2, s98
	v_lshl_add_u32 v245, v245, 2, s99
	ds_read_b32 v124, v244
	ds_read_b32 v108, v245
	v_add_u32_e32 v243, 0xffffffef, v67
	v_min_u32_e32 v244, 0x7f, v243
	v_min_u32_e32 v245, 0x9f, v243
	v_lshl_add_u32 v244, v244, 2, s98
	v_lshl_add_u32 v245, v245, 2, s99
	ds_read_b32 v125, v244
	ds_read_b32 v109, v245
	v_add_u32_e32 v243, 0xffffffee, v67
	v_min_u32_e32 v244, 0x7f, v243
	v_min_u32_e32 v245, 0x9f, v243
	v_lshl_add_u32 v244, v244, 2, s98
	v_lshl_add_u32 v245, v245, 2, s99
	ds_read_b32 v126, v244
	ds_read_b32 v110, v245
	v_add_u32_e32 v243, 0xffffffed, v67
	v_min_u32_e32 v244, 0x7f, v243
	v_min_u32_e32 v245, 0x9f, v243
	v_lshl_add_u32 v244, v244, 2, s98
	v_lshl_add_u32 v245, v245, 2, s99
	ds_read_b32 v127, v244
	ds_read_b32 v111, v245
	v_add_u32_e32 v243, 0xffffffe8, v67
	v_min_u32_e32 v244, 0x7f, v243
	v_min_u32_e32 v245, 0x9f, v243
	v_lshl_add_u32 v244, v244, 2, s98
	v_lshl_add_u32 v245, v245, 2, s99
	ds_read_b32 v128, v244
	ds_read_b32 v112, v245
	v_add_u32_e32 v243, 0xffffffe7, v67
	v_min_u32_e32 v244, 0x7f, v243
	v_min_u32_e32 v245, 0x9f, v243
	v_lshl_add_u32 v244, v244, 2, s98
	v_lshl_add_u32 v245, v245, 2, s99
	ds_read_b32 v129, v244
	ds_read_b32 v113, v245
	v_add_u32_e32 v243, 0xffffffe6, v67
	v_min_u32_e32 v244, 0x7f, v243
	v_min_u32_e32 v245, 0x9f, v243
	v_lshl_add_u32 v244, v244, 2, s98
	v_lshl_add_u32 v245, v245, 2, s99
	ds_read_b32 v130, v244
	ds_read_b32 v114, v245
	v_add_u32_e32 v243, 0xffffffe5, v67
	v_min_u32_e32 v244, 0x7f, v243
	v_min_u32_e32 v245, 0x9f, v243
	v_lshl_add_u32 v244, v244, 2, s98
	v_lshl_add_u32 v245, v245, 2, s99
	ds_read_b32 v131, v244
	ds_read_b32 v115, v245
	s_waitcnt lgkmcnt(0)
	v_add_u32_e32 v243, 0, v67
	v_add_f32_e32 v116, v84, v116
	v_cmp_lt_i32_e32 vcc, -1, v243
	v_cndmask_b32_e32 v116, v246, v116, vcc
	v_add_f32_e32 v100, v68, v100
	v_cmp_lt_i32_e32 vcc, 31, v243
	v_cndmask_b32_e32 v100, v246, v100, vcc
	v_add_u32_e32 v243, -1, v67
	v_add_f32_e32 v117, v85, v117
	v_cmp_lt_i32_e32 vcc, -1, v243
	v_cndmask_b32_e32 v117, v246, v117, vcc
	v_add_f32_e32 v101, v69, v101
	v_cmp_lt_i32_e32 vcc, 31, v243
	v_cndmask_b32_e32 v101, v246, v101, vcc
	v_add_u32_e32 v243, -2, v67
	v_add_f32_e32 v118, v86, v118
	v_cmp_lt_i32_e32 vcc, -1, v243
	v_cndmask_b32_e32 v118, v246, v118, vcc
	v_add_f32_e32 v102, v70, v102
	v_cmp_lt_i32_e32 vcc, 31, v243
	v_cndmask_b32_e32 v102, v246, v102, vcc
	v_add_u32_e32 v243, -3, v67
	v_add_f32_e32 v119, v87, v119
	v_cmp_lt_i32_e32 vcc, -1, v243
	v_cndmask_b32_e32 v119, v246, v119, vcc
	v_add_f32_e32 v103, v71, v103
	v_cmp_lt_i32_e32 vcc, 31, v243
	v_cndmask_b32_e32 v103, v246, v103, vcc
	v_add_u32_e32 v243, -8, v67
	v_add_f32_e32 v120, v88, v120
	v_cmp_lt_i32_e32 vcc, -1, v243
	v_cndmask_b32_e32 v120, v246, v120, vcc
	v_add_f32_e32 v104, v72, v104
	v_cmp_lt_i32_e32 vcc, 31, v243
	v_cndmask_b32_e32 v104, v246, v104, vcc
	v_add_u32_e32 v243, -9, v67
	v_add_f32_e32 v121, v89, v121
	v_cmp_lt_i32_e32 vcc, -1, v243
	v_cndmask_b32_e32 v121, v246, v121, vcc
	v_add_f32_e32 v105, v73, v105
	v_cmp_lt_i32_e32 vcc, 31, v243
	v_cndmask_b32_e32 v105, v246, v105, vcc
	v_add_u32_e32 v243, -10, v67
	v_add_f32_e32 v122, v90, v122
	v_cmp_lt_i32_e32 vcc, -1, v243
	v_cndmask_b32_e32 v122, v246, v122, vcc
	v_add_f32_e32 v106, v74, v106
	v_cmp_lt_i32_e32 vcc, 31, v243
	v_cndmask_b32_e32 v106, v246, v106, vcc
	v_add_u32_e32 v243, -11, v67
	v_add_f32_e32 v123, v91, v123
	v_cmp_lt_i32_e32 vcc, -1, v243
	v_cndmask_b32_e32 v123, v246, v123, vcc
	v_add_f32_e32 v107, v75, v107
	v_cmp_lt_i32_e32 vcc, 31, v243
	v_cndmask_b32_e32 v107, v246, v107, vcc
	v_add_u32_e32 v243, -16, v67
	v_add_f32_e32 v124, v92, v124
	v_cmp_lt_i32_e32 vcc, -1, v243
	v_cndmask_b32_e32 v124, v246, v124, vcc
	v_add_f32_e32 v108, v76, v108
	v_cmp_lt_i32_e32 vcc, 31, v243
	v_cndmask_b32_e32 v108, v246, v108, vcc
	v_add_u32_e32 v243, 0xffffffef, v67
	v_add_f32_e32 v125, v93, v125
	v_cmp_lt_i32_e32 vcc, -1, v243
	v_cndmask_b32_e32 v125, v246, v125, vcc
	v_add_f32_e32 v109, v77, v109
	v_cmp_lt_i32_e32 vcc, 31, v243
	v_cndmask_b32_e32 v109, v246, v109, vcc
	v_add_u32_e32 v243, 0xffffffee, v67
	v_add_f32_e32 v126, v94, v126
	v_cmp_lt_i32_e32 vcc, -1, v243
	v_cndmask_b32_e32 v126, v246, v126, vcc
	v_add_f32_e32 v110, v78, v110
	v_cmp_lt_i32_e32 vcc, 31, v243
	v_cndmask_b32_e32 v110, v246, v110, vcc
	v_add_u32_e32 v243, 0xffffffed, v67
	v_add_f32_e32 v127, v95, v127
	v_cmp_lt_i32_e32 vcc, -1, v243
	v_cndmask_b32_e32 v127, v246, v127, vcc
	v_add_f32_e32 v111, v79, v111
	v_cmp_lt_i32_e32 vcc, 31, v243
	v_cndmask_b32_e32 v111, v246, v111, vcc
	v_add_u32_e32 v243, 0xffffffe8, v67
	v_add_f32_e32 v128, v96, v128
	v_cmp_lt_i32_e32 vcc, -1, v243
	v_cndmask_b32_e32 v128, v246, v128, vcc
	v_add_f32_e32 v112, v80, v112
	v_cmp_lt_i32_e32 vcc, 31, v243
	v_cndmask_b32_e32 v112, v246, v112, vcc
	v_add_u32_e32 v243, 0xffffffe7, v67
	v_add_f32_e32 v129, v97, v129
	v_cmp_lt_i32_e32 vcc, -1, v243
	v_cndmask_b32_e32 v129, v246, v129, vcc
	v_add_f32_e32 v113, v81, v113
	v_cmp_lt_i32_e32 vcc, 31, v243
	v_cndmask_b32_e32 v113, v246, v113, vcc
	v_add_u32_e32 v243, 0xffffffe6, v67
	v_add_f32_e32 v130, v98, v130
	v_cmp_lt_i32_e32 vcc, -1, v243
	v_cndmask_b32_e32 v130, v246, v130, vcc
	v_add_f32_e32 v114, v82, v114
	v_cmp_lt_i32_e32 vcc, 31, v243
	v_cndmask_b32_e32 v114, v246, v114, vcc
	v_add_u32_e32 v243, 0xffffffe5, v67
	v_add_f32_e32 v131, v99, v131
	v_cmp_lt_i32_e32 vcc, -1, v243
	v_cndmask_b32_e32 v131, v246, v131, vcc
	v_add_f32_e32 v115, v83, v115
	v_cmp_lt_i32_e32 vcc, 31, v243
	v_cndmask_b32_e32 v115, v246, v115, vcc
